# diff2 X row sums via v_pk_add_f32 pairs (7 fewer adds per sub-tile) on top of v25
# baseline (speedup 1.0000x reference)
; __device__ __forceinline__ void d2_softmax(v16f& S, const float c1, const LAS float* tp, float& m, float& l, v16f (&O)[4], v8s (&P)[2]) {
;     ...
;     const float mc = m;
;     float ps = 0.f;
; #pragma unroll
;     for (int i = 0; i < 16; ++i) { S[i] = __builtin_amdgcn_exp2f(S[i] - mc); ps += S[i]; }
;     l += ps;
.Ld2x0_a:
	v_sub_f32_e32 v66, v0, v184
	v_exp_f32_e32 v66, v66
	v_sub_f32_e32 v67, v135, v184
	v_exp_f32_e32 v67, v67
	v_sub_f32_e32 v68, v68, v184
	v_exp_f32_e32 v68, v68
	v_sub_f32_e32 v69, v131, v184
	v_exp_f32_e32 v69, v69
	v_sub_f32_e32 v70, v70, v184
	v_exp_f32_e32 v70, v70
	v_sub_f32_e32 v71, v133, v184
	v_exp_f32_e32 v71, v71
	v_sub_f32_e32 v72, v72, v184
	v_exp_f32_e32 v72, v72
	v_sub_f32_e32 v73, v137, v184
	v_pk_add_f32 v[252:253], v[66:67], v[68:69]
	v_exp_f32_e32 v73, v73
	v_sub_f32_e32 v74, v74, v184
	v_exp_f32_e32 v74, v74
	v_sub_f32_e32 v75, v139, v184
	v_pk_add_f32 v[252:253], v[252:253], v[70:71]
	v_exp_f32_e32 v75, v75
	v_sub_f32_e32 v76, v76, v184
	v_exp_f32_e32 v76, v76
	v_sub_f32_e32 v77, v141, v184
	v_pk_add_f32 v[252:253], v[252:253], v[72:73]
	v_exp_f32_e32 v77, v77
	v_sub_f32_e32 v78, v78, v184
	v_exp_f32_e32 v78, v78
	v_sub_f32_e32 v79, v143, v184
	v_pk_add_f32 v[252:253], v[252:253], v[74:75]
	v_exp_f32_e32 v79, v79
	v_sub_f32_e32 v80, v80, v184
	v_exp_f32_e32 v80, v80
	v_sub_f32_e32 v81, v145, v184
	v_pk_add_f32 v[252:253], v[252:253], v[76:77]
	v_exp_f32_e32 v81, v81
	s_branch .Ld2x0_s0t

; #define LAS __attribute__((address_space(3)))
; __device__ __forceinline__ void d2_softmax(v16f& S, const float c1, const LAS float* tp, float& m, float& l, v16f (&O)[4], v8s (&P)[2]) {
;     float tmax = NEGBIG;
; #pragma unroll
;     for (int i = 0; i < 16; ++i) { S[i] = S[i] * c1 + tp[(i & 3) + 8 * (i >> 2)]; tmax = fmaxf(tmax, S[i]); }
;     tmax = fmaxf(tmax, __shfl_xor(tmax, 32));
;     const float mo = m;
;     if (__any(tmax > mo + 8.f)) {
;         const float mn = (tmax > mo + 8.f) ? tmax : mo;
;         const float alpha = __builtin_amdgcn_exp2f(mo - mn);
;         l *= alpha;
; #pragma unroll
;         for (int eb = 0; eb < 4; ++eb)
; #pragma unroll
;             for (int i = 0; i < 16; ++i) O[eb][i] *= alpha;
;         m = mn;
;     }
;     const float mc = m;
;     float ps = 0.f;
; #pragma unroll
;     for (int i = 0; i < 16; ++i) { S[i] = __builtin_amdgcn_exp2f(S[i] - mc); ps += S[i]; }
;     l += ps;
.Ld2x0_f0a:
	v_sub_f32_e32 v134, v134, v184
	v_fmamk_f32 v66, v66, 0x3e38aa3b, v134
	v_exp_f32_e32 v66, v66
	v_fmamk_f32 v67, v67, 0x3e38aa3b, v134
	v_exp_f32_e32 v67, v67
	v_fmamk_f32 v68, v68, 0x3e38aa3b, v134
	v_exp_f32_e32 v68, v68
	v_fmamk_f32 v69, v69, 0x3e38aa3b, v134
	v_exp_f32_e32 v69, v69
	v_fmamk_f32 v70, v70, 0x3e38aa3b, v134
	v_exp_f32_e32 v70, v70
	v_fmamk_f32 v71, v71, 0x3e38aa3b, v134
	v_exp_f32_e32 v71, v71
	v_fmamk_f32 v72, v72, 0x3e38aa3b, v134
	v_exp_f32_e32 v72, v72
	v_fmamk_f32 v73, v73, 0x3e38aa3b, v134
	v_pk_add_f32 v[252:253], v[66:67], v[68:69]
	v_exp_f32_e32 v73, v73
	v_fmamk_f32 v74, v74, 0x3e38aa3b, v134
	v_exp_f32_e32 v74, v74
	v_fmamk_f32 v75, v75, 0x3e38aa3b, v134
	v_pk_add_f32 v[252:253], v[252:253], v[70:71]
	v_exp_f32_e32 v75, v75
	v_fmamk_f32 v76, v76, 0x3e38aa3b, v134
	v_exp_f32_e32 v76, v76
	v_fmamk_f32 v77, v77, 0x3e38aa3b, v134
	v_pk_add_f32 v[252:253], v[252:253], v[72:73]
	v_exp_f32_e32 v77, v77
	v_fmamk_f32 v78, v78, 0x3e38aa3b, v134
	v_exp_f32_e32 v78, v78
	v_fmamk_f32 v79, v79, 0x3e38aa3b, v134
	v_pk_add_f32 v[252:253], v[252:253], v[74:75]
	v_exp_f32_e32 v79, v79
	v_fmamk_f32 v80, v80, 0x3e38aa3b, v134
	v_exp_f32_e32 v80, v80
	v_fmamk_f32 v81, v81, 0x3e38aa3b, v134
	v_pk_add_f32 v[252:253], v[252:253], v[76:77]
	v_exp_f32_e32 v81, v81
.Ld2x0_s0t:
	v_pk_add_f32 v[252:253], v[252:253], v[78:79]
	v_pk_add_f32 v[252:253], v[252:253], v[80:81]
	v_add_f32_e32 v0, v252, v253
	v_add_f32_e32 v0, v154, v0
	s_waitcnt lgkmcnt(0)
	s_bitcmp1_b64 s[100:101], s99
	s_cbranch_scc1 .Ld2x0_c1f
	v_fmamk_f32 v82, v82, 0x3e38aa3b, v186
	v_fmac_f32_e32 v187, 0x3e38aa3b, v83
	v_max3_f32 v83, v82, s15, v187
	v_fmamk_f32 v84, v84, 0x3e38aa3b, v188
	v_fmac_f32_e32 v189, 0x3e38aa3b, v85
	v_max3_f32 v83, v83, v84, v189
	v_fmamk_f32 v86, v86, 0x3e38aa3b, v190
	v_fmac_f32_e32 v191, 0x3e38aa3b, v87
	v_max3_f32 v83, v83, v86, v191
	v_fmamk_f32 v88, v88, 0x3e38aa3b, v192
	v_fmac_f32_e32 v193, 0x3e38aa3b, v89
	v_max3_f32 v83, v83, v88, v193
	v_fmamk_f32 v90, v90, 0x3e38aa3b, v194
	v_fmac_f32_e32 v195, 0x3e38aa3b, v91
	v_max3_f32 v83, v83, v90, v195
	v_fmamk_f32 v92, v92, 0x3e38aa3b, v196
	v_fmac_f32_e32 v197, 0x3e38aa3b, v93
	v_max3_f32 v83, v83, v92, v197
	v_fmamk_f32 v94, v94, 0x3e38aa3b, v198
	v_fmac_f32_e32 v199, 0x3e38aa3b, v95
	v_max3_f32 v83, v83, v94, v199
	v_fmamk_f32 v96, v96, 0x3e38aa3b, v200
	v_fmac_f32_e32 v201, 0x3e38aa3b, v97
	v_max3_f32 v83, v83, v96, v201
	v_cmp_gt_f32_e32 vcc, v83, v130
	s_cbranch_vccz .Ld2x0_b
	v_mov_b32_e32 v85, v83
	s_nop 1
	v_permlane32_swap_b32_e32 v85, v83
	v_max_f32_e32 v83, v83, v85
	v_cmp_gt_f32_e32 vcc, v83, v130
	s_nop 1
	v_cndmask_b32_e32 v83, v184, v83, vcc
	v_sub_f32_e32 v85, v184, v83
	v_exp_f32_e32 v130, v85
	v_mov_b32_e32 v184, v83
	v_mul_f32_e32 v0, v0, v130
	v_pk_mul_f32 v[64:65], v[64:65], v[130:131] op_sel_hi:[1,0]
	v_pk_mul_f32 v[62:63], v[62:63], v[130:131] op_sel_hi:[1,0]
	v_pk_mul_f32 v[60:61], v[60:61], v[130:131] op_sel_hi:[1,0]
	v_pk_mul_f32 v[58:59], v[58:59], v[130:131] op_sel_hi:[1,0]
	v_pk_mul_f32 v[56:57], v[56:57], v[130:131] op_sel_hi:[1,0]
	v_pk_mul_f32 v[54:55], v[54:55], v[130:131] op_sel_hi:[1,0]
	v_pk_mul_f32 v[52:53], v[52:53], v[130:131] op_sel_hi:[1,0]
	v_pk_mul_f32 v[50:51], v[50:51], v[130:131] op_sel_hi:[1,0]
	v_pk_mul_f32 v[48:49], v[48:49], v[130:131] op_sel_hi:[1,0]
	v_pk_mul_f32 v[46:47], v[46:47], v[130:131] op_sel_hi:[1,0]
	v_pk_mul_f32 v[44:45], v[44:45], v[130:131] op_sel_hi:[1,0]
	v_pk_mul_f32 v[42:43], v[42:43], v[130:131] op_sel_hi:[1,0]
	v_pk_mul_f32 v[40:41], v[40:41], v[130:131] op_sel_hi:[1,0]
	v_pk_mul_f32 v[38:39], v[38:39], v[130:131] op_sel_hi:[1,0]
	v_pk_mul_f32 v[36:37], v[36:37], v[130:131] op_sel_hi:[1,0]
	v_pk_mul_f32 v[34:35], v[34:35], v[130:131] op_sel_hi:[1,0]
	v_pk_mul_f32 v[32:33], v[32:33], v[130:131] op_sel_hi:[1,0]
	v_pk_mul_f32 v[30:31], v[30:31], v[130:131] op_sel_hi:[1,0]
	v_pk_mul_f32 v[28:29], v[28:29], v[130:131] op_sel_hi:[1,0]
	v_pk_mul_f32 v[26:27], v[26:27], v[130:131] op_sel_hi:[1,0]
	v_pk_mul_f32 v[24:25], v[24:25], v[130:131] op_sel_hi:[1,0]
	v_pk_mul_f32 v[22:23], v[22:23], v[130:131] op_sel_hi:[1,0]
	v_pk_mul_f32 v[20:21], v[20:21], v[130:131] op_sel_hi:[1,0]
	v_pk_mul_f32 v[18:19], v[18:19], v[130:131] op_sel_hi:[1,0]
	v_pk_mul_f32 v[16:17], v[16:17], v[130:131] op_sel_hi:[1,0]
	v_pk_mul_f32 v[14:15], v[14:15], v[130:131] op_sel_hi:[1,0]
	v_pk_mul_f32 v[12:13], v[12:13], v[130:131] op_sel_hi:[1,0]
	v_pk_mul_f32 v[10:11], v[10:11], v[130:131] op_sel_hi:[1,0]
	v_pk_mul_f32 v[8:9], v[8:9], v[130:131] op_sel_hi:[1,0]
	v_pk_mul_f32 v[6:7], v[6:7], v[130:131] op_sel_hi:[1,0]
	v_pk_mul_f32 v[4:5], v[4:5], v[130:131] op_sel_hi:[1,0]
	v_pk_mul_f32 v[2:3], v[2:3], v[130:131] op_sel_hi:[1,0]
.Ld2x0_b:
	v_sub_f32_e32 v82, v82, v184
	v_exp_f32_e32 v82, v82
	v_sub_f32_e32 v83, v187, v184
	v_exp_f32_e32 v83, v83
	v_sub_f32_e32 v84, v84, v184
	v_exp_f32_e32 v84, v84
	v_sub_f32_e32 v85, v189, v184
	v_exp_f32_e32 v85, v85
	v_sub_f32_e32 v86, v86, v184
	v_exp_f32_e32 v86, v86
	v_sub_f32_e32 v87, v191, v184
	v_exp_f32_e32 v87, v87
	v_sub_f32_e32 v88, v88, v184
	v_exp_f32_e32 v88, v88
	v_sub_f32_e32 v89, v193, v184
	v_pk_add_f32 v[254:255], v[82:83], v[84:85]
	v_exp_f32_e32 v89, v89
	v_sub_f32_e32 v90, v90, v184
	v_exp_f32_e32 v90, v90
	v_sub_f32_e32 v91, v195, v184
	v_pk_add_f32 v[254:255], v[254:255], v[86:87]
	v_exp_f32_e32 v91, v91
	v_sub_f32_e32 v92, v92, v184
	v_exp_f32_e32 v92, v92
	v_sub_f32_e32 v93, v197, v184
	v_pk_add_f32 v[254:255], v[254:255], v[88:89]
	v_exp_f32_e32 v93, v93
	v_sub_f32_e32 v94, v94, v184
	v_exp_f32_e32 v94, v94
	v_sub_f32_e32 v95, v199, v184
	v_pk_add_f32 v[254:255], v[254:255], v[90:91]
	v_exp_f32_e32 v95, v95
	v_sub_f32_e32 v96, v96, v184
	v_exp_f32_e32 v96, v96
	v_sub_f32_e32 v97, v201, v184
	v_pk_add_f32 v[254:255], v[254:255], v[92:93]
	v_exp_f32_e32 v97, v97
	s_branch .Ld2x0_cv

; __device__ __forceinline__ unsigned pk2(float lo, float hi) { v2f v = {lo, hi}; return __builtin_bit_cast(unsigned, __builtin_convertvector(v, v2bf)); }
; __device__ __forceinline__ void d2_softmax(v16f& S, const float c1, const LAS float* tp, float& m, float& l, v16f (&O)[4], v8s (&P)[2]) {
;     ...
;     const float mc = m;
;     float ps = 0.f;
; #pragma unroll
;     for (int i = 0; i < 16; ++i) { S[i] = __builtin_amdgcn_exp2f(S[i] - mc); ps += S[i]; }
;     l += ps;
; #pragma unroll
;     for (int s2 = 0; s2 < 2; ++s2) { v4u w; w.x = pk2(S[8 * s2 + 0], S[8 * s2 + 1]); w.y = pk2(S[8 * s2 + 2], S[8 * s2 + 3]); w.z = pk2(S[8 * s2 + 4], S[8 * s2 + 5]); w.w = pk2(S[8 * s2 + 6], S[8 * s2 + 7]);
;         P[s2] = __builtin_bit_cast(v8s, w); }
.Ld2x0_f1a:
	v_sub_f32_e32 v186, v186, v184
	v_fmamk_f32 v82, v82, 0x3e38aa3b, v186
	v_exp_f32_e32 v82, v82
	v_fmamk_f32 v83, v83, 0x3e38aa3b, v186
	v_exp_f32_e32 v83, v83
	v_fmamk_f32 v84, v84, 0x3e38aa3b, v186
	v_exp_f32_e32 v84, v84
	v_fmamk_f32 v85, v85, 0x3e38aa3b, v186
	v_exp_f32_e32 v85, v85
	v_fmamk_f32 v86, v86, 0x3e38aa3b, v186
	v_exp_f32_e32 v86, v86
	v_fmamk_f32 v87, v87, 0x3e38aa3b, v186
	v_exp_f32_e32 v87, v87
	v_fmamk_f32 v88, v88, 0x3e38aa3b, v186
	v_exp_f32_e32 v88, v88
	v_fmamk_f32 v89, v89, 0x3e38aa3b, v186
	v_pk_add_f32 v[254:255], v[82:83], v[84:85]
	v_exp_f32_e32 v89, v89
	v_fmamk_f32 v90, v90, 0x3e38aa3b, v186
	v_exp_f32_e32 v90, v90
	v_fmamk_f32 v91, v91, 0x3e38aa3b, v186
	v_pk_add_f32 v[254:255], v[254:255], v[86:87]
	v_exp_f32_e32 v91, v91
	v_fmamk_f32 v92, v92, 0x3e38aa3b, v186
	v_exp_f32_e32 v92, v92
	v_fmamk_f32 v93, v93, 0x3e38aa3b, v186
	v_pk_add_f32 v[254:255], v[254:255], v[88:89]
	v_exp_f32_e32 v93, v93
	v_fmamk_f32 v94, v94, 0x3e38aa3b, v186
	v_exp_f32_e32 v94, v94
	v_fmamk_f32 v95, v95, 0x3e38aa3b, v186
	v_pk_add_f32 v[254:255], v[254:255], v[90:91]
	v_exp_f32_e32 v95, v95
	v_fmamk_f32 v96, v96, 0x3e38aa3b, v186
	v_exp_f32_e32 v96, v96
	v_fmamk_f32 v97, v97, 0x3e38aa3b, v186
	v_pk_add_f32 v[254:255], v[254:255], v[92:93]
	v_exp_f32_e32 v97, v97
.Ld2x0_cv:
	v_cvt_pk_bf16_f32 v134, v66, v67
	v_cvt_pk_bf16_f32 v135, v68, v69
	v_pk_add_f32 v[254:255], v[254:255], v[94:95]
	v_cvt_pk_bf16_f32 v136, v70, v71
	v_cvt_pk_bf16_f32 v137, v72, v73
	v_pk_add_f32 v[254:255], v[254:255], v[96:97]
	v_cvt_pk_bf16_f32 v130, v74, v75
	v_cvt_pk_bf16_f32 v131, v76, v77
	v_cvt_pk_bf16_f32 v132, v78, v79
	v_cvt_pk_bf16_f32 v133, v80, v81
	v_add_f32_e32 v156, v254, v255
	v_add_f32_e32 v154, v0, v156
	v_cvt_pk_bf16_f32 v142, v82, v83
	v_cvt_pk_bf16_f32 v143, v84, v85
	v_cvt_pk_bf16_f32 v144, v86, v87
	v_cvt_pk_bf16_f32 v145, v88, v89
	v_cvt_pk_bf16_f32 v138, v90, v91
	v_cvt_pk_bf16_f32 v139, v92, v93
	v_cvt_pk_bf16_f32 v140, v94, v95
	v_cvt_pk_bf16_f32 v141, v96, v97
	s_setprio 0
